# out-projection GEMM main loop (loop-edge): next-iteration pointer set behind the last segment's MFMAs, two-branch rescale test on a free SGPR, trip counter stepped in place
# speedup vs baseline: 1.0062x; 1.0062x over previous
.LBB0_1256:
	s_ashr_i32 s91, s90, 31
	s_lshl_b64 s[22:23], s[90:91], 20
	s_add_u32 s56, s38, s22
	s_addc_u32 s57, s39, s23
	s_and_b64 s[22:23], s[6:7], exec
	s_cselect_b32 s15, s57, s93
	s_cselect_b32 s91, s56, s92
	s_ashr_i32 s89, s88, 31
	s_lshl_b64 s[22:23], s[88:89], 20
	s_add_u32 s94, s40, s22
	s_addc_u32 s95, s41, s23
	s_and_b64 s[22:23], s[6:7], exec
	s_cselect_b32 s89, s95, s97
	s_cselect_b32 s8, s94, s96
	s_mov_b32 s82, 0
	s_movk_i32 s44, 0xe200
	s_mov_b64 s[76:77], 0x100
	v_mov_b64_e32 v[134:135], v[132:133]
	v_mov_b64_e32 v[136:137], v[130:131]
	s_add_u32 s22, s92, s76
	s_addc_u32 s23, s93, s77
	s_add_u32 s80, s96, s76
	s_addc_u32 s81, s97, s77
	s_cmp_eq_u32 s44, 0
	s_cselect_b32 s23, s15, s23
	s_cselect_b32 s22, s91, s22
	s_cselect_b32 vcc_hi, s89, s81
	s_cselect_b32 vcc_lo, s8, s80
	s_add_u32 s80, s92, s76
	s_addc_u32 s81, s93, s77
	s_sub_u32 s80, s80, 0x80
	s_subb_u32 s81, s81, 0
.LBB0_1257:
	s_bitcmp1_b32 s82, 1
	s_cbranch_scc1 .LBB0_1259
	s_add_i32 s32, s82, -4
	s_cmp_gt_u32 s32, 12
	s_cbranch_scc1 .LBB0_1259
	v_add_u32_e32 v141, s44, v139
	v_add_u32_e32 v141, 0x21a00, v141
	ds_read_b32 v142, v141
	ds_read_b32 v144, v141 offset:64
	ds_read_b32 v146, v141 offset:128
	ds_read_b32 v148, v141 offset:192
	ds_read_b32 v150, v141 offset:512
	ds_read_b32 v152, v141 offset:576
	ds_read_b32 v154, v141 offset:640
	ds_read_b32 v156, v141 offset:704
	s_waitcnt lgkmcnt(7)
	v_pk_mul_f32 v[126:127], v[126:127], v[142:143] op_sel_hi:[1,0]
	v_pk_mul_f32 v[124:125], v[124:125], v[142:143] op_sel_hi:[1,0]
	v_pk_mul_f32 v[122:123], v[122:123], v[142:143] op_sel_hi:[1,0]
	v_pk_mul_f32 v[120:121], v[120:121], v[142:143] op_sel_hi:[1,0]
	v_pk_mul_f32 v[118:119], v[118:119], v[142:143] op_sel_hi:[1,0]
	v_pk_mul_f32 v[116:117], v[116:117], v[142:143] op_sel_hi:[1,0]
	v_pk_mul_f32 v[114:115], v[114:115], v[142:143] op_sel_hi:[1,0]
	v_pk_mul_f32 v[112:113], v[112:113], v[142:143] op_sel_hi:[1,0]
	s_waitcnt lgkmcnt(6)
	v_pk_mul_f32 v[110:111], v[110:111], v[144:145] op_sel_hi:[1,0]
	v_pk_mul_f32 v[108:109], v[108:109], v[144:145] op_sel_hi:[1,0]
	v_pk_mul_f32 v[106:107], v[106:107], v[144:145] op_sel_hi:[1,0]
	v_pk_mul_f32 v[104:105], v[104:105], v[144:145] op_sel_hi:[1,0]
	v_pk_mul_f32 v[102:103], v[102:103], v[144:145] op_sel_hi:[1,0]
	v_pk_mul_f32 v[100:101], v[100:101], v[144:145] op_sel_hi:[1,0]
	v_pk_mul_f32 v[98:99], v[98:99], v[144:145] op_sel_hi:[1,0]
	v_pk_mul_f32 v[96:97], v[96:97], v[144:145] op_sel_hi:[1,0]
	s_waitcnt lgkmcnt(5)
	v_pk_mul_f32 v[94:95], v[94:95], v[146:147] op_sel_hi:[1,0]
	v_pk_mul_f32 v[92:93], v[92:93], v[146:147] op_sel_hi:[1,0]
	v_pk_mul_f32 v[90:91], v[90:91], v[146:147] op_sel_hi:[1,0]
	v_pk_mul_f32 v[88:89], v[88:89], v[146:147] op_sel_hi:[1,0]
	v_pk_mul_f32 v[86:87], v[86:87], v[146:147] op_sel_hi:[1,0]
	v_pk_mul_f32 v[84:85], v[84:85], v[146:147] op_sel_hi:[1,0]
	v_pk_mul_f32 v[82:83], v[82:83], v[146:147] op_sel_hi:[1,0]
	v_pk_mul_f32 v[80:81], v[80:81], v[146:147] op_sel_hi:[1,0]
	s_waitcnt lgkmcnt(4)
	v_pk_mul_f32 v[78:79], v[78:79], v[148:149] op_sel_hi:[1,0]
	v_pk_mul_f32 v[76:77], v[76:77], v[148:149] op_sel_hi:[1,0]
	v_pk_mul_f32 v[74:75], v[74:75], v[148:149] op_sel_hi:[1,0]
	v_pk_mul_f32 v[72:73], v[72:73], v[148:149] op_sel_hi:[1,0]
	v_pk_mul_f32 v[70:71], v[70:71], v[148:149] op_sel_hi:[1,0]
	v_pk_mul_f32 v[68:69], v[68:69], v[148:149] op_sel_hi:[1,0]
	v_pk_mul_f32 v[66:67], v[66:67], v[148:149] op_sel_hi:[1,0]
	v_pk_mul_f32 v[64:65], v[64:65], v[148:149] op_sel_hi:[1,0]
	s_waitcnt lgkmcnt(3)
	v_pk_mul_f32 v[62:63], v[62:63], v[150:151] op_sel_hi:[1,0]
	v_pk_mul_f32 v[60:61], v[60:61], v[150:151] op_sel_hi:[1,0]
	v_pk_mul_f32 v[58:59], v[58:59], v[150:151] op_sel_hi:[1,0]
	v_pk_mul_f32 v[56:57], v[56:57], v[150:151] op_sel_hi:[1,0]
	v_pk_mul_f32 v[54:55], v[54:55], v[150:151] op_sel_hi:[1,0]
	v_pk_mul_f32 v[52:53], v[52:53], v[150:151] op_sel_hi:[1,0]
	v_pk_mul_f32 v[50:51], v[50:51], v[150:151] op_sel_hi:[1,0]
	v_pk_mul_f32 v[48:49], v[48:49], v[150:151] op_sel_hi:[1,0]
	s_waitcnt lgkmcnt(2)
	v_pk_mul_f32 v[46:47], v[46:47], v[152:153] op_sel_hi:[1,0]
	v_pk_mul_f32 v[44:45], v[44:45], v[152:153] op_sel_hi:[1,0]
	v_pk_mul_f32 v[42:43], v[42:43], v[152:153] op_sel_hi:[1,0]
	v_pk_mul_f32 v[40:41], v[40:41], v[152:153] op_sel_hi:[1,0]
	v_pk_mul_f32 v[38:39], v[38:39], v[152:153] op_sel_hi:[1,0]
	v_pk_mul_f32 v[36:37], v[36:37], v[152:153] op_sel_hi:[1,0]
	v_pk_mul_f32 v[34:35], v[34:35], v[152:153] op_sel_hi:[1,0]
	v_pk_mul_f32 v[32:33], v[32:33], v[152:153] op_sel_hi:[1,0]
	s_waitcnt lgkmcnt(1)
	v_pk_mul_f32 v[30:31], v[30:31], v[154:155] op_sel_hi:[1,0]
	v_pk_mul_f32 v[28:29], v[28:29], v[154:155] op_sel_hi:[1,0]
	v_pk_mul_f32 v[26:27], v[26:27], v[154:155] op_sel_hi:[1,0]
	v_pk_mul_f32 v[24:25], v[24:25], v[154:155] op_sel_hi:[1,0]
	v_pk_mul_f32 v[22:23], v[22:23], v[154:155] op_sel_hi:[1,0]
	v_pk_mul_f32 v[20:21], v[20:21], v[154:155] op_sel_hi:[1,0]
	v_pk_mul_f32 v[18:19], v[18:19], v[154:155] op_sel_hi:[1,0]
	v_pk_mul_f32 v[16:17], v[16:17], v[154:155] op_sel_hi:[1,0]
	s_waitcnt lgkmcnt(0)
	v_pk_mul_f32 v[14:15], v[14:15], v[156:157] op_sel_hi:[1,0]
	v_pk_mul_f32 v[12:13], v[12:13], v[156:157] op_sel_hi:[1,0]
	v_pk_mul_f32 v[10:11], v[10:11], v[156:157] op_sel_hi:[1,0]
	v_pk_mul_f32 v[8:9], v[8:9], v[156:157] op_sel_hi:[1,0]
	v_pk_mul_f32 v[6:7], v[6:7], v[156:157] op_sel_hi:[1,0]
	v_pk_mul_f32 v[4:5], v[4:5], v[156:157] op_sel_hi:[1,0]
	v_pk_mul_f32 v[2:3], v[2:3], v[156:157] op_sel_hi:[1,0]
	v_pk_mul_f32 v[0:1], v[0:1], v[156:157] op_sel_hi:[1,0]
.LBB0_1259:
	ds_read_b128 v[142:145], v222
	ds_read_b128 v[146:149], v222 offset:1024
	ds_read_b128 v[150:153], v222 offset:2048
	ds_read_b128 v[154:157], v222 offset:3072
	ds_read_b128 v[158:161], v223
	ds_read_b128 v[162:165], v223 offset:1024
	ds_read_b128 v[166:169], v223 offset:2048
	ds_read_b128 v[170:173], v223 offset:3072
	s_mov_b32 m0, s9
	ds_read_b128 v[174:177], v140
	ds_read_b128 v[178:181], v140 offset:1024
	ds_read_b128 v[182:185], v140 offset:2048
	ds_read_b128 v[186:189], v140 offset:3072
	ds_read_b128 v[190:193], v140 offset:4096
	ds_read_b128 v[194:197], v140 offset:5120
	ds_read_b128 v[198:201], v140 offset:6144
	ds_read_b128 v[202:205], v140 offset:7168
	global_load_lds_dwordx4 v208, s[80:81]
	s_mov_b32 m0, s12
	s_nop 0
	global_load_lds_dwordx4 v128, s[80:81]
	s_add_i32 m0, s45, 0xc000
	s_nop 0
	global_load_lds_dwordx4 v136, s[92:93]
	s_add_i32 m0, s45, 0xe000
	s_nop 0
	global_load_lds_dwordx4 v134, s[92:93]
	s_waitcnt vmcnt(8)
	s_waitcnt lgkmcnt(0)
	s_barrier
	v_mfma_f32_16x16x32_bf16 v[124:127], v[142:145], v[174:177], v[124:127]
	v_mfma_f32_16x16x32_bf16 v[120:123], v[150:153], v[174:177], v[120:123]
	v_mfma_f32_16x16x32_bf16 v[108:111], v[142:145], v[182:185], v[108:111]
	v_mfma_f32_16x16x32_bf16 v[104:107], v[150:153], v[182:185], v[104:107]
	v_mfma_f32_16x16x32_bf16 v[92:95], v[142:145], v[190:193], v[92:95]
	v_mfma_f32_16x16x32_bf16 v[88:91], v[150:153], v[190:193], v[88:91]
	v_mfma_f32_16x16x32_bf16 v[76:79], v[142:145], v[198:201], v[76:79]
	v_mfma_f32_16x16x32_bf16 v[72:75], v[150:153], v[198:201], v[72:75]
	v_mfma_f32_16x16x32_bf16 v[124:127], v[146:149], v[178:181], v[124:127]
	v_mfma_f32_16x16x32_bf16 v[120:123], v[154:157], v[178:181], v[120:123]
	v_mfma_f32_16x16x32_bf16 v[108:111], v[146:149], v[186:189], v[108:111]
	v_mfma_f32_16x16x32_bf16 v[104:107], v[154:157], v[186:189], v[104:107]
	v_mfma_f32_16x16x32_bf16 v[92:95], v[146:149], v[194:197], v[92:95]
	v_mfma_f32_16x16x32_bf16 v[88:91], v[154:157], v[194:197], v[88:91]
	v_mfma_f32_16x16x32_bf16 v[76:79], v[146:149], v[202:205], v[76:79]
	v_mfma_f32_16x16x32_bf16 v[72:75], v[154:157], v[202:205], v[72:75]
	v_mfma_f32_16x16x32_bf16 v[116:119], v[158:161], v[174:177], v[116:119]
	v_mfma_f32_16x16x32_bf16 v[112:115], v[166:169], v[174:177], v[112:115]
	v_mfma_f32_16x16x32_bf16 v[100:103], v[158:161], v[182:185], v[100:103]
	v_mfma_f32_16x16x32_bf16 v[96:99], v[166:169], v[182:185], v[96:99]
	v_mfma_f32_16x16x32_bf16 v[84:87], v[158:161], v[190:193], v[84:87]
	v_mfma_f32_16x16x32_bf16 v[80:83], v[166:169], v[190:193], v[80:83]
	v_mfma_f32_16x16x32_bf16 v[68:71], v[158:161], v[198:201], v[68:71]
	v_mfma_f32_16x16x32_bf16 v[64:67], v[166:169], v[198:201], v[64:67]
	v_mfma_f32_16x16x32_bf16 v[116:119], v[162:165], v[178:181], v[116:119]
	v_mfma_f32_16x16x32_bf16 v[112:115], v[170:173], v[178:181], v[112:115]
	v_mfma_f32_16x16x32_bf16 v[100:103], v[162:165], v[186:189], v[100:103]
	v_mfma_f32_16x16x32_bf16 v[96:99], v[170:173], v[186:189], v[96:99]
	v_mfma_f32_16x16x32_bf16 v[84:87], v[162:165], v[194:197], v[84:87]
	v_mfma_f32_16x16x32_bf16 v[80:83], v[170:173], v[194:197], v[80:83]
	v_mfma_f32_16x16x32_bf16 v[68:71], v[162:165], v[202:205], v[68:71]
	v_mfma_f32_16x16x32_bf16 v[64:67], v[170:173], v[202:205], v[64:67]
	s_barrier
	s_add_i32 m0, s43, 0x10000
	ds_read_b128 v[174:177], v140 offset:16384
	ds_read_b128 v[178:181], v140 offset:17408
	ds_read_b128 v[182:185], v140 offset:18432
	ds_read_b128 v[186:189], v140 offset:19456
	ds_read_b128 v[190:193], v140 offset:20480
	ds_read_b128 v[194:197], v140 offset:21504
	ds_read_b128 v[198:201], v140 offset:22528
	ds_read_b128 v[202:205], v140 offset:23552
	global_load_lds_dwordx4 v208, vcc
	s_add_i32 m0, s43, 0x12000
	s_add_u32 s80, vcc_lo, 0x80000
	s_addc_u32 s81, vcc_hi, 0
	global_load_lds_dwordx4 v128, vcc
	s_add_i32 m0, s43, 0x14000
	s_nop 0
	global_load_lds_dwordx4 v208, s[80:81]
	s_add_i32 m0, s43, 0x16000
	s_nop 0
	global_load_lds_dwordx4 v128, s[80:81]
	s_waitcnt vmcnt(6)
	s_waitcnt lgkmcnt(0)
	s_barrier
	v_mfma_f32_16x16x32_bf16 v[60:63], v[142:145], v[174:177], v[60:63]
	v_mfma_f32_16x16x32_bf16 v[56:59], v[150:153], v[174:177], v[56:59]
	v_mfma_f32_16x16x32_bf16 v[44:47], v[142:145], v[182:185], v[44:47]
	v_mfma_f32_16x16x32_bf16 v[40:43], v[150:153], v[182:185], v[40:43]
	v_mfma_f32_16x16x32_bf16 v[28:31], v[142:145], v[190:193], v[28:31]
	v_mfma_f32_16x16x32_bf16 v[24:27], v[150:153], v[190:193], v[24:27]
	v_mfma_f32_16x16x32_bf16 v[12:15], v[142:145], v[198:201], v[12:15]
	v_mfma_f32_16x16x32_bf16 v[8:11], v[150:153], v[198:201], v[8:11]
	v_mfma_f32_16x16x32_bf16 v[60:63], v[146:149], v[178:181], v[60:63]
	v_mfma_f32_16x16x32_bf16 v[56:59], v[154:157], v[178:181], v[56:59]
	v_mfma_f32_16x16x32_bf16 v[44:47], v[146:149], v[186:189], v[44:47]
	v_mfma_f32_16x16x32_bf16 v[40:43], v[154:157], v[186:189], v[40:43]
	v_mfma_f32_16x16x32_bf16 v[28:31], v[146:149], v[194:197], v[28:31]
	v_mfma_f32_16x16x32_bf16 v[24:27], v[154:157], v[194:197], v[24:27]
	v_mfma_f32_16x16x32_bf16 v[12:15], v[146:149], v[202:205], v[12:15]
	v_mfma_f32_16x16x32_bf16 v[8:11], v[154:157], v[202:205], v[8:11]
	v_mfma_f32_16x16x32_bf16 v[52:55], v[158:161], v[174:177], v[52:55]
	v_mfma_f32_16x16x32_bf16 v[48:51], v[166:169], v[174:177], v[48:51]
	v_mfma_f32_16x16x32_bf16 v[36:39], v[158:161], v[182:185], v[36:39]
	v_mfma_f32_16x16x32_bf16 v[32:35], v[166:169], v[182:185], v[32:35]
	v_mfma_f32_16x16x32_bf16 v[20:23], v[158:161], v[190:193], v[20:23]
	v_mfma_f32_16x16x32_bf16 v[16:19], v[166:169], v[190:193], v[16:19]
	v_mfma_f32_16x16x32_bf16 v[4:7], v[158:161], v[198:201], v[4:7]
	v_mfma_f32_16x16x32_bf16 v[0:3], v[166:169], v[198:201], v[0:3]
	v_mfma_f32_16x16x32_bf16 v[52:55], v[162:165], v[178:181], v[52:55]
	v_mfma_f32_16x16x32_bf16 v[48:51], v[170:173], v[178:181], v[48:51]
	v_mfma_f32_16x16x32_bf16 v[36:39], v[162:165], v[186:189], v[36:39]
	v_mfma_f32_16x16x32_bf16 v[32:35], v[170:173], v[186:189], v[32:35]
	v_mfma_f32_16x16x32_bf16 v[20:23], v[162:165], v[194:197], v[20:23]
	v_mfma_f32_16x16x32_bf16 v[16:19], v[170:173], v[194:197], v[16:19]
	v_mfma_f32_16x16x32_bf16 v[4:7], v[162:165], v[202:205], v[4:7]
	v_mfma_f32_16x16x32_bf16 v[0:3], v[170:173], v[202:205], v[0:3]
	s_barrier
	ds_read_b128 v[142:145], v224
	ds_read_b128 v[146:149], v224 offset:1024
	ds_read_b128 v[150:153], v224 offset:2048
	ds_read_b128 v[154:157], v224 offset:3072
	ds_read_b128 v[158:161], v225
	ds_read_b128 v[162:165], v225 offset:1024
	ds_read_b128 v[166:169], v225 offset:2048
	ds_read_b128 v[170:173], v225 offset:3072
	ds_read_b128 v[174:177], v140 offset:32768
	ds_read_b128 v[178:181], v140 offset:33792
	ds_read_b128 v[182:185], v140 offset:34816
	ds_read_b128 v[186:189], v140 offset:35840
	ds_read_b128 v[190:193], v140 offset:36864
	ds_read_b128 v[194:197], v140 offset:37888
	ds_read_b128 v[198:201], v140 offset:38912
	ds_read_b128 v[202:205], v140 offset:39936
	s_mov_b32 m0, s45
	s_nop 0
	global_load_lds_dwordx4 v208, s[22:23]
	s_mov_b32 m0, s52
	s_nop 0
	global_load_lds_dwordx4 v128, s[22:23]
	s_mov_b32 m0, s53
	s_add_u32 s22, s22, 0x80000
	s_addc_u32 s23, s23, 0
	global_load_lds_dwordx4 v208, s[22:23]
	s_mov_b32 m0, s85
	s_nop 0
	global_load_lds_dwordx4 v128, s[22:23]
	s_waitcnt vmcnt(8)
	s_waitcnt lgkmcnt(0)
	s_barrier
	v_mfma_f32_16x16x32_bf16 v[124:127], v[142:145], v[174:177], v[124:127]
	v_mfma_f32_16x16x32_bf16 v[120:123], v[150:153], v[174:177], v[120:123]
	v_mfma_f32_16x16x32_bf16 v[108:111], v[142:145], v[182:185], v[108:111]
	v_mfma_f32_16x16x32_bf16 v[104:107], v[150:153], v[182:185], v[104:107]
	v_mfma_f32_16x16x32_bf16 v[92:95], v[142:145], v[190:193], v[92:95]
	v_mfma_f32_16x16x32_bf16 v[88:91], v[150:153], v[190:193], v[88:91]
	v_mfma_f32_16x16x32_bf16 v[76:79], v[142:145], v[198:201], v[76:79]
	v_mfma_f32_16x16x32_bf16 v[72:75], v[150:153], v[198:201], v[72:75]
	v_mfma_f32_16x16x32_bf16 v[124:127], v[146:149], v[178:181], v[124:127]
	v_mfma_f32_16x16x32_bf16 v[120:123], v[154:157], v[178:181], v[120:123]
	v_mfma_f32_16x16x32_bf16 v[108:111], v[146:149], v[186:189], v[108:111]
	v_mfma_f32_16x16x32_bf16 v[104:107], v[154:157], v[186:189], v[104:107]
	v_mfma_f32_16x16x32_bf16 v[92:95], v[146:149], v[194:197], v[92:95]
	v_mfma_f32_16x16x32_bf16 v[88:91], v[154:157], v[194:197], v[88:91]
	v_mfma_f32_16x16x32_bf16 v[76:79], v[146:149], v[202:205], v[76:79]
	v_mfma_f32_16x16x32_bf16 v[72:75], v[154:157], v[202:205], v[72:75]
	v_mfma_f32_16x16x32_bf16 v[116:119], v[158:161], v[174:177], v[116:119]
	v_mfma_f32_16x16x32_bf16 v[112:115], v[166:169], v[174:177], v[112:115]
	v_mfma_f32_16x16x32_bf16 v[100:103], v[158:161], v[182:185], v[100:103]
	v_mfma_f32_16x16x32_bf16 v[96:99], v[166:169], v[182:185], v[96:99]
	v_mfma_f32_16x16x32_bf16 v[84:87], v[158:161], v[190:193], v[84:87]
	v_mfma_f32_16x16x32_bf16 v[80:83], v[166:169], v[190:193], v[80:83]
	v_mfma_f32_16x16x32_bf16 v[68:71], v[158:161], v[198:201], v[68:71]
	v_mfma_f32_16x16x32_bf16 v[64:67], v[166:169], v[198:201], v[64:67]
	v_mfma_f32_16x16x32_bf16 v[116:119], v[162:165], v[178:181], v[116:119]
	v_mfma_f32_16x16x32_bf16 v[112:115], v[170:173], v[178:181], v[112:115]
	v_mfma_f32_16x16x32_bf16 v[100:103], v[162:165], v[186:189], v[100:103]
	v_mfma_f32_16x16x32_bf16 v[96:99], v[170:173], v[186:189], v[96:99]
	v_mfma_f32_16x16x32_bf16 v[84:87], v[162:165], v[194:197], v[84:87]
	v_mfma_f32_16x16x32_bf16 v[80:83], v[170:173], v[194:197], v[80:83]
	v_mfma_f32_16x16x32_bf16 v[68:71], v[162:165], v[202:205], v[68:71]
	v_mfma_f32_16x16x32_bf16 v[64:67], v[170:173], v[202:205], v[64:67]
	s_barrier
	s_add_i32 m0, s43, 0x17f80
	ds_read_b128 v[174:177], v140 offset:49152
	ds_read_b128 v[178:181], v140 offset:50176
	ds_read_b128 v[182:185], v140 offset:51200
	ds_read_b128 v[186:189], v140 offset:52224
	ds_read_b128 v[190:193], v140 offset:53248
	ds_read_b128 v[194:197], v140 offset:54272
	ds_read_b128 v[198:201], v140 offset:55296
	ds_read_b128 v[202:205], v140 offset:56320
	global_load_lds_dwordx4 v208, vcc offset:128
	s_add_i32 m0, s43, 0x19f80
	s_add_u32 s22, vcc_lo, 0x80080
	s_addc_u32 s23, vcc_hi, 0
	global_load_lds_dwordx4 v128, vcc offset:128
	s_add_i32 m0, s43, 0x1c000
	s_nop 0
	global_load_lds_dwordx4 v208, s[22:23]
	s_add_i32 m0, s43, 0x1e000
	s_nop 0
	global_load_lds_dwordx4 v128, s[22:23]
	s_waitcnt vmcnt(6)
	s_waitcnt lgkmcnt(0)
	s_barrier
	v_mfma_f32_16x16x32_bf16 v[60:63], v[142:145], v[174:177], v[60:63]
	v_mfma_f32_16x16x32_bf16 v[56:59], v[150:153], v[174:177], v[56:59]
	s_addk_i32 s44, 0x200
	v_mfma_f32_16x16x32_bf16 v[44:47], v[142:145], v[182:185], v[44:47]
	v_mfma_f32_16x16x32_bf16 v[40:43], v[150:153], v[182:185], v[40:43]
	s_add_u32 s76, s76, 0x100
	s_addc_u32 s77, s77, 0
	v_mfma_f32_16x16x32_bf16 v[28:31], v[142:145], v[190:193], v[28:31]
	v_mfma_f32_16x16x32_bf16 v[24:27], v[150:153], v[190:193], v[24:27]
	v_lshl_add_u64 v[136:137], v[136:137], 0, s[58:59]
	v_mfma_f32_16x16x32_bf16 v[12:15], v[142:145], v[198:201], v[12:15]
	v_mfma_f32_16x16x32_bf16 v[8:11], v[150:153], v[198:201], v[8:11]
	v_lshl_add_u64 v[134:135], v[134:135], 0, s[58:59]
	v_mfma_f32_16x16x32_bf16 v[60:63], v[146:149], v[178:181], v[60:63]
	v_mfma_f32_16x16x32_bf16 v[56:59], v[154:157], v[178:181], v[56:59]
	s_add_u32 s22, s92, s76
	s_addc_u32 s23, s93, s77
	v_mfma_f32_16x16x32_bf16 v[44:47], v[146:149], v[186:189], v[44:47]
	v_mfma_f32_16x16x32_bf16 v[40:43], v[154:157], v[186:189], v[40:43]
	s_add_u32 s80, s96, s76
	s_addc_u32 s81, s97, s77
	v_mfma_f32_16x16x32_bf16 v[28:31], v[146:149], v[194:197], v[28:31]
	v_mfma_f32_16x16x32_bf16 v[24:27], v[154:157], v[194:197], v[24:27]
	s_cmp_eq_u32 s44, 0
	s_cselect_b32 s23, s15, s23
	s_cselect_b32 s22, s91, s22
	s_cselect_b32 vcc_hi, s89, s81
	s_cselect_b32 vcc_lo, s8, s80
	v_mfma_f32_16x16x32_bf16 v[12:15], v[146:149], v[202:205], v[12:15]
	v_mfma_f32_16x16x32_bf16 v[8:11], v[154:157], v[202:205], v[8:11]
	s_add_u32 s80, s92, s76
	s_addc_u32 s81, s93, s77
	s_sub_u32 s80, s80, 0x80
	s_subb_u32 s81, s81, 0
	v_mfma_f32_16x16x32_bf16 v[52:55], v[158:161], v[174:177], v[52:55]
	v_mfma_f32_16x16x32_bf16 v[48:51], v[166:169], v[174:177], v[48:51]
	v_mfma_f32_16x16x32_bf16 v[36:39], v[158:161], v[182:185], v[36:39]
	v_mfma_f32_16x16x32_bf16 v[32:35], v[166:169], v[182:185], v[32:35]
	v_mfma_f32_16x16x32_bf16 v[20:23], v[158:161], v[190:193], v[20:23]
	v_mfma_f32_16x16x32_bf16 v[16:19], v[166:169], v[190:193], v[16:19]
	v_mfma_f32_16x16x32_bf16 v[4:7], v[158:161], v[198:201], v[4:7]
	v_mfma_f32_16x16x32_bf16 v[0:3], v[166:169], v[198:201], v[0:3]
	v_mfma_f32_16x16x32_bf16 v[52:55], v[162:165], v[178:181], v[52:55]
	v_mfma_f32_16x16x32_bf16 v[48:51], v[170:173], v[178:181], v[48:51]
	v_mfma_f32_16x16x32_bf16 v[36:39], v[162:165], v[186:189], v[36:39]
	v_mfma_f32_16x16x32_bf16 v[32:35], v[170:173], v[186:189], v[32:35]
	v_mfma_f32_16x16x32_bf16 v[20:23], v[162:165], v[194:197], v[20:23]
	v_mfma_f32_16x16x32_bf16 v[16:19], v[170:173], v[194:197], v[16:19]
	v_mfma_f32_16x16x32_bf16 v[4:7], v[162:165], v[202:205], v[4:7]
	v_mfma_f32_16x16x32_bf16 v[0:3], v[170:173], v[202:205], v[0:3]
	s_barrier
	s_cmp_gt_u32 s82, 29
	s_cbranch_scc1 .LBB0_1261
	s_add_i32 s82, s82, 2
	s_branch .LBB0_1257
